# GEMM1/GEMM3 k-loops rotated: next-tile fragment reads issued right after the barrier, B fragments double-buffered, 4 A buffers, LDS-DMA issues interleaved with MFMAs
# speedup vs baseline: 1.0006x; 1.0006x over previous
; #define G_WAIT_V0() asm volatile("s_waitcnt vmcnt(0)" ::: "memory")
; __device__ __forceinline__ void g_kloop(const u16* __restrict__ Ab, const u16* __restrict__ Bb, const int K, char* smem, ...
;     ...
;   for (int t = 0; t < nt; ++t) {
;     const int cur = t & 1;
;     if (t + 1 < nt) G_STAGE(cur ^ 1, t + 1)
;     else if (has_next) {
;       char* sa_ = smem + wid * 1024;
;       char* sb_ = sa_ + G_TILE_B;
;       __builtin_amdgcn_global_load_lds((const unsigned*)(nA + o0), (unsigned*)(sa_), 16, 0, 0);
;       __builtin_amdgcn_global_load_lds((const unsigned*)(nB + o0), (unsigned*)(sb_), 16, 0, 0);
;       __builtin_amdgcn_global_load_lds((const unsigned*)(nA + o1), (unsigned*)(sa_ + 8192), 16, 0, 0);
;       __builtin_amdgcn_global_load_lds((const unsigned*)(nB + o1), (unsigned*)(sb_ + 8192), 16, 0, 0);
;       __builtin_amdgcn_global_load_lds((const unsigned*)(nA + o2), (unsigned*)(sa_ + 16384), 16, 0, 0);
;       __builtin_amdgcn_global_load_lds((const unsigned*)(nB + o2), (unsigned*)(sb_ + 16384), 16, 0, 0);
;       __builtin_amdgcn_global_load_lds((const unsigned*)(nA + o3), (unsigned*)(sa_ + 24576), 16, 0, 0);
;       __builtin_amdgcn_global_load_lds((const unsigned*)(nB + o3), (unsigned*)(sb_ + 24576), 16, 0, 0);
;     }
;     const char* sa = smem + cur * G_STAGE_B;
;     const char* sb = sa + G_TILE_B;
; #pragma unroll
;     for (int ks = 0; ks < 2; ++ks) {
;       s16x8 At[8], Bf[4];
; #pragma unroll
;       for (int m = 0; m < 8; ++m) At[m] = *(const s16x8*)(sa + g_lds_byte(wr * 128 + m * 16 + fr, ks * 32 + fq * 8));
; #pragma unroll
;       for (int n = 0; n < 4; ++n) Bf[n] = *(const s16x8*)(sb + g_lds_byte(wc * 64 + n * 16 + fr, ks * 32 + fq * 8));
; #pragma unroll
;       for (int m = 0; m < 8; ++m)
; #pragma unroll
;         for (int n = 0; n < 4; ++n)
;           acc[m][n] = __builtin_amdgcn_mfma_f32_16x16x32_bf16(__builtin_bit_cast(bf16x8, Bf[n]), __builtin_bit_cast(bf16x8, At[m]), acc[m][n], 0, 0, 0);
;     }
;     G_WAIT_V0();
;     __syncthreads();
;   }
.LBB0_119:
	s_and_b32 s14, s1, 0x10000
	v_or_b32_e32 v96, s14, v170
	v_add_u32_e32 v182, v96, v171
	v_add_u32_e32 v96, v96, v172
	ds_read_b128 v[130:133], v96 offset:32768
	ds_read_b128 v[138:141], v96 offset:34816
	ds_read_b128 v[174:177], v96 offset:36864
	ds_read_b128 v[178:181], v96 offset:38912
	ds_read_b128 v[134:137], v182
	ds_read_b128 v[204:207], v182 offset:2048
	ds_read_b128 v[208:211], v182 offset:4096
	ds_read_b128 v[212:215], v182 offset:6144
.Lmy_k1_top:
	s_and_b32 s5, s1, 0x10000
	s_xor_b32 s14, s5, 0x10000
	v_add_u32_e32 v252, s14, v166
	s_waitcnt lgkmcnt(3)
	v_mfma_f32_16x16x32_bf16 v[4:7], v[130:133], v[134:137], v[4:7]
	v_mfma_f32_16x16x32_bf16 v[114:117], v[138:141], v[134:137], v[114:117]
	v_mfma_f32_16x16x32_bf16 v[110:113], v[174:177], v[134:137], v[110:113]
	v_mfma_f32_16x16x32_bf16 v[106:109], v[178:181], v[134:137], v[106:109]
	ds_read_b128 v[134:137], v182 offset:8192
	v_readfirstlane_b32 s5, v252
	s_mov_b32 m0, s5
	v_lshl_add_u64 v[220:221], v[150:151], 0, s[12:13]
	global_load_lds_dwordx4 v[220:221], off
	s_waitcnt lgkmcnt(3)
	v_mfma_f32_16x16x32_bf16 v[102:105], v[130:133], v[204:207], v[102:105]
	v_mfma_f32_16x16x32_bf16 v[92:95], v[138:141], v[204:207], v[92:95]
	v_mfma_f32_16x16x32_bf16 v[76:79], v[174:177], v[204:207], v[76:79]
	v_mfma_f32_16x16x32_bf16 v[48:51], v[178:181], v[204:207], v[48:51]
	ds_read_b128 v[204:207], v182 offset:10240
	s_add_u32 m0, s5, 0x8000
	v_lshl_add_u64 v[220:221], v[158:159], 0, s[12:13]
	global_load_lds_dwordx4 v[220:221], off
	s_waitcnt lgkmcnt(3)
	v_mfma_f32_16x16x32_bf16 v[98:101], v[130:133], v[208:211], v[98:101]
	v_mfma_f32_16x16x32_bf16 v[84:87], v[138:141], v[208:211], v[84:87]
	v_mfma_f32_16x16x32_bf16 v[64:67], v[174:177], v[208:211], v[64:67]
	v_mfma_f32_16x16x32_bf16 v[36:39], v[178:181], v[208:211], v[36:39]
	ds_read_b128 v[208:211], v182 offset:12288
	ds_read_b128 v[216:219], v96 offset:33792
	s_add_u32 m0, s5, 0x2000
	v_lshl_add_u64 v[220:221], v[152:153], 0, s[12:13]
	global_load_lds_dwordx4 v[220:221], off
	s_waitcnt lgkmcnt(4)
	v_mfma_f32_16x16x32_bf16 v[88:91], v[130:133], v[212:215], v[88:91]
	v_mfma_f32_16x16x32_bf16 v[72:75], v[138:141], v[212:215], v[72:75]
	v_mfma_f32_16x16x32_bf16 v[52:55], v[174:177], v[212:215], v[52:55]
	v_mfma_f32_16x16x32_bf16 v[24:27], v[178:181], v[212:215], v[24:27]
	ds_read_b128 v[212:215], v182 offset:14336
	ds_read_b128 v[230:233], v96 offset:35840
	s_add_u32 m0, s5, 0xa000
	v_lshl_add_u64 v[220:221], v[160:161], 0, s[12:13]
	global_load_lds_dwordx4 v[220:221], off
	s_waitcnt lgkmcnt(5)
	v_mfma_f32_16x16x32_bf16 v[80:83], v[130:133], v[134:137], v[80:83]
	v_mfma_f32_16x16x32_bf16 v[60:63], v[138:141], v[134:137], v[60:63]
	v_mfma_f32_16x16x32_bf16 v[40:43], v[174:177], v[134:137], v[40:43]
	v_mfma_f32_16x16x32_bf16 v[16:19], v[178:181], v[134:137], v[16:19]
	ds_read_b128 v[134:137], v182 offset:1024
	ds_read_b128 v[244:247], v96 offset:37888
	s_add_u32 m0, s5, 0x4000
	v_lshl_add_u64 v[220:221], v[154:155], 0, s[12:13]
	global_load_lds_dwordx4 v[220:221], off
	s_waitcnt lgkmcnt(6)
	v_mfma_f32_16x16x32_bf16 v[68:71], v[130:133], v[204:207], v[68:71]
	v_mfma_f32_16x16x32_bf16 v[44:47], v[138:141], v[204:207], v[44:47]
	v_mfma_f32_16x16x32_bf16 v[28:31], v[174:177], v[204:207], v[28:31]
	v_mfma_f32_16x16x32_bf16 v[12:15], v[178:181], v[204:207], v[12:15]
	ds_read_b128 v[204:207], v182 offset:3072
	ds_read_b128 v[248:251], v96 offset:39936
	s_add_u32 m0, s5, 0xc000
	v_lshl_add_u64 v[220:221], v[162:163], 0, s[12:13]
	global_load_lds_dwordx4 v[220:221], off
	s_waitcnt lgkmcnt(7)
	v_mfma_f32_16x16x32_bf16 v[56:59], v[130:133], v[208:211], v[56:59]
	v_mfma_f32_16x16x32_bf16 v[32:35], v[138:141], v[208:211], v[32:35]
	v_mfma_f32_16x16x32_bf16 v[20:23], v[174:177], v[208:211], v[20:23]
	v_mfma_f32_16x16x32_bf16 v[8:11], v[178:181], v[208:211], v[8:11]
	ds_read_b128 v[208:211], v182 offset:5120
	s_add_u32 m0, s5, 0x6000
	v_lshl_add_u64 v[220:221], v[156:157], 0, s[12:13]
	global_load_lds_dwordx4 v[220:221], off
	s_waitcnt lgkmcnt(6)
	v_mfma_f32_16x16x32_bf16 v[122:125], v[130:133], v[212:215], v[122:125]
	v_mfma_f32_16x16x32_bf16 v[118:121], v[138:141], v[212:215], v[118:121]
	v_mfma_f32_16x16x32_bf16 v[126:129], v[174:177], v[212:215], v[126:129]
	v_mfma_f32_16x16x32_bf16 v[0:3], v[178:181], v[212:215], v[0:3]
	ds_read_b128 v[212:215], v182 offset:7168
	s_add_u32 m0, s5, 0xe000
	v_lshl_add_u64 v[220:221], v[164:165], 0, s[12:13]
	global_load_lds_dwordx4 v[220:221], off
	s_waitcnt lgkmcnt(5)
	v_mfma_f32_16x16x32_bf16 v[4:7], v[216:219], v[134:137], v[4:7]
	v_mfma_f32_16x16x32_bf16 v[114:117], v[230:233], v[134:137], v[114:117]
	s_waitcnt lgkmcnt(4)
	v_mfma_f32_16x16x32_bf16 v[110:113], v[244:247], v[134:137], v[110:113]
	s_waitcnt lgkmcnt(2)
	v_mfma_f32_16x16x32_bf16 v[106:109], v[248:251], v[134:137], v[106:109]
	ds_read_b128 v[134:137], v182 offset:9216
	v_mfma_f32_16x16x32_bf16 v[102:105], v[216:219], v[204:207], v[102:105]
	v_mfma_f32_16x16x32_bf16 v[92:95], v[230:233], v[204:207], v[92:95]
	v_mfma_f32_16x16x32_bf16 v[76:79], v[244:247], v[204:207], v[76:79]
	v_mfma_f32_16x16x32_bf16 v[48:51], v[248:251], v[204:207], v[48:51]
	ds_read_b128 v[204:207], v182 offset:11264
	s_waitcnt lgkmcnt(3)
	v_mfma_f32_16x16x32_bf16 v[98:101], v[216:219], v[208:211], v[98:101]
	v_mfma_f32_16x16x32_bf16 v[84:87], v[230:233], v[208:211], v[84:87]
	v_mfma_f32_16x16x32_bf16 v[64:67], v[244:247], v[208:211], v[64:67]
	v_mfma_f32_16x16x32_bf16 v[36:39], v[248:251], v[208:211], v[36:39]
	ds_read_b128 v[208:211], v182 offset:13312
	s_waitcnt lgkmcnt(3)
	v_mfma_f32_16x16x32_bf16 v[88:91], v[216:219], v[212:215], v[88:91]
	v_mfma_f32_16x16x32_bf16 v[72:75], v[230:233], v[212:215], v[72:75]
	v_mfma_f32_16x16x32_bf16 v[52:55], v[244:247], v[212:215], v[52:55]
	v_mfma_f32_16x16x32_bf16 v[24:27], v[248:251], v[212:215], v[24:27]
	ds_read_b128 v[212:215], v182 offset:15360
	s_waitcnt lgkmcnt(3)
	v_mfma_f32_16x16x32_bf16 v[80:83], v[216:219], v[134:137], v[80:83]
	v_mfma_f32_16x16x32_bf16 v[60:63], v[230:233], v[134:137], v[60:63]
	v_mfma_f32_16x16x32_bf16 v[40:43], v[244:247], v[134:137], v[40:43]
	v_mfma_f32_16x16x32_bf16 v[16:19], v[248:251], v[134:137], v[16:19]
	s_waitcnt lgkmcnt(2)
	v_mfma_f32_16x16x32_bf16 v[68:71], v[216:219], v[204:207], v[68:71]
	v_mfma_f32_16x16x32_bf16 v[44:47], v[230:233], v[204:207], v[44:47]
	v_mfma_f32_16x16x32_bf16 v[28:31], v[244:247], v[204:207], v[28:31]
	v_mfma_f32_16x16x32_bf16 v[12:15], v[248:251], v[204:207], v[12:15]
	s_waitcnt vmcnt(0)
	s_waitcnt vmcnt(0) lgkmcnt(0)
	s_barrier
; #define G_WAIT_V0() asm volatile("s_waitcnt vmcnt(0)" ::: "memory")
; __device__ __forceinline__ void g_kloop(const u16* __restrict__ Ab, const u16* __restrict__ Bb, const int K, char* smem, ...
;     ...
;   for (int t = 0; t < nt; ++t) {
;     const int cur = t & 1;
;     if (t + 1 < nt) G_STAGE(cur ^ 1, t + 1)
;     else if (has_next) {
;       char* sa_ = smem + wid * 1024;
;       char* sb_ = sa_ + G_TILE_B;
;       __builtin_amdgcn_global_load_lds((const unsigned*)(nA + o0), (unsigned*)(sa_), 16, 0, 0);
;       __builtin_amdgcn_global_load_lds((const unsigned*)(nB + o0), (unsigned*)(sb_), 16, 0, 0);
;       __builtin_amdgcn_global_load_lds((const unsigned*)(nA + o1), (unsigned*)(sa_ + 8192), 16, 0, 0);
;       __builtin_amdgcn_global_load_lds((const unsigned*)(nB + o1), (unsigned*)(sb_ + 8192), 16, 0, 0);
;       __builtin_amdgcn_global_load_lds((const unsigned*)(nA + o2), (unsigned*)(sa_ + 16384), 16, 0, 0);
;       __builtin_amdgcn_global_load_lds((const unsigned*)(nB + o2), (unsigned*)(sb_ + 16384), 16, 0, 0);
;       __builtin_amdgcn_global_load_lds((const unsigned*)(nA + o3), (unsigned*)(sa_ + 24576), 16, 0, 0);
;       __builtin_amdgcn_global_load_lds((const unsigned*)(nB + o3), (unsigned*)(sb_ + 24576), 16, 0, 0);
;     }
;     const char* sa = smem + cur * G_STAGE_B;
;     const char* sb = sa + G_TILE_B;
; #pragma unroll
;     for (int ks = 0; ks < 2; ++ks) {
;       s16x8 At[8], Bf[4];
; #pragma unroll
;       for (int m = 0; m < 8; ++m) At[m] = *(const s16x8*)(sa + g_lds_byte(wr * 128 + m * 16 + fr, ks * 32 + fq * 8));
; #pragma unroll
;       for (int n = 0; n < 4; ++n) Bf[n] = *(const s16x8*)(sb + g_lds_byte(wc * 64 + n * 16 + fr, ks * 32 + fq * 8));
; #pragma unroll
;       for (int m = 0; m < 8; ++m)
; #pragma unroll
;         for (int n = 0; n < 4; ++n)
;           acc[m][n] = __builtin_amdgcn_mfma_f32_16x16x32_bf16(__builtin_bit_cast(bf16x8, Bf[n]), __builtin_bit_cast(bf16x8, At[m]), acc[m][n], 0, 0, 0);
;     }
;     G_WAIT_V0();
;     __syncthreads();
;   }
	s_add_i32 s1, s1, 0x10000
	s_add_u32 s12, s12, 0x80
	s_addc_u32 s13, s13, 0
	s_and_b32 s14, s1, 0x10000
	v_or_b32_e32 v96, s14, v170
	v_add_u32_e32 v182, v96, v171
	v_add_u32_e32 v96, v96, v172
	ds_read_b128 v[130:133], v96 offset:32768
	ds_read_b128 v[138:141], v96 offset:34816
	ds_read_b128 v[174:177], v96 offset:36864
	ds_read_b128 v[178:181], v96 offset:38912
	ds_read_b128 v[134:137], v182
	ds_read_b128 v[204:207], v182 offset:2048
	v_mfma_f32_16x16x32_bf16 v[56:59], v[216:219], v[208:211], v[56:59]
	v_mfma_f32_16x16x32_bf16 v[32:35], v[230:233], v[208:211], v[32:35]
	v_mfma_f32_16x16x32_bf16 v[20:23], v[244:247], v[208:211], v[20:23]
	v_mfma_f32_16x16x32_bf16 v[8:11], v[248:251], v[208:211], v[8:11]
	ds_read_b128 v[208:211], v182 offset:4096
	v_mfma_f32_16x16x32_bf16 v[122:125], v[216:219], v[212:215], v[122:125]
	v_mfma_f32_16x16x32_bf16 v[118:121], v[230:233], v[212:215], v[118:121]
	v_mfma_f32_16x16x32_bf16 v[126:129], v[244:247], v[212:215], v[126:129]
	v_mfma_f32_16x16x32_bf16 v[0:3], v[248:251], v[212:215], v[0:3]
	ds_read_b128 v[212:215], v182 offset:6144
	s_cmpk_lg_i32 s12, 0x780
	s_cbranch_scc1 .Lmy_k1_top
	s_waitcnt lgkmcnt(0)
	s_andn2_b64 vcc, exec, s[10:11]
	s_cbranch_vccnz .LBB0_122
	s_lshl_b32 s10, s25, 8
	s_ashr_i32 s11, s10, 31
	s_lshl_b64 s[10:11], s[10:11], 11
	s_add_u32 s10, s86, s10
	s_addc_u32 s11, s87, s11
	s_lshl_b32 s12, s24, 8
	s_ashr_i32 s13, s12, 31
	s_lshl_b64 s[12:13], s[12:13], 11
	s_add_u32 s12, s20, s12
	v_lshlrev_b64 v[130:131], 1, v[142:143]
	v_add_u32_e32 v151, 0x8000, v166
	v_readfirstlane_b32 s1, v166
	s_addc_u32 s13, s21, s13
	v_lshl_add_u64 v[132:133], s[10:11], 0, v[130:131]
	v_add_u32_e32 v150, 0x2000, v166
	s_mov_b32 m0, s1
	v_readfirstlane_b32 s1, v151
	v_lshl_add_u64 v[130:131], s[12:13], 0, v[130:131]
	v_lshlrev_b64 v[134:135], 1, v[144:145]
	v_lshlrev_b64 v[142:143], 1, v[148:149]
	v_add_u32_e32 v149, 0xa000, v166
	global_load_lds_dwordx4 v[132:133], off
	s_mov_b32 m0, s1
	v_readfirstlane_b32 s1, v150
	v_lshl_add_u64 v[136:137], s[10:11], 0, v[134:135]
	v_add_u32_e32 v148, 0x4000, v166
	global_load_lds_dwordx4 v[130:131], off
	s_mov_b32 m0, s1
	v_readfirstlane_b32 s1, v149
	v_lshl_add_u64 v[134:135], s[12:13], 0, v[134:135]
	v_lshlrev_b64 v[138:139], 1, v[146:147]
	v_add_u32_e32 v147, 0xc000, v166
	global_load_lds_dwordx4 v[136:137], off
	s_mov_b32 m0, s1
	v_readfirstlane_b32 s1, v148
	v_lshl_add_u64 v[140:141], s[10:11], 0, v[138:139]
	v_add_u32_e32 v146, 0x6000, v166
	global_load_lds_dwordx4 v[134:135], off
	s_mov_b32 m0, s1
	v_readfirstlane_b32 s1, v147
	v_lshl_add_u64 v[138:139], s[12:13], 0, v[138:139]
	v_add_u32_e32 v96, 0xe000, v166
	global_load_lds_dwordx4 v[140:141], off
	s_mov_b32 m0, s1
	v_readfirstlane_b32 s1, v146
	v_lshl_add_u64 v[144:145], s[10:11], 0, v[142:143]
	global_load_lds_dwordx4 v[138:139], off
	s_mov_b32 m0, s1
	v_readfirstlane_b32 s1, v96
	v_lshl_add_u64 v[142:143], s[12:13], 0, v[142:143]
	global_load_lds_dwordx4 v[144:145], off
	s_mov_b32 m0, s1
	s_nop 0
	global_load_lds_dwordx4 v[142:143], off

; #define G_WAIT_V0() asm volatile("s_waitcnt vmcnt(0)" ::: "memory")
; __device__ __forceinline__ void g_kloop(const u16* __restrict__ Ab, const u16* __restrict__ Bb, const int K, char* smem, ...
;     ...
;   for (int t = 0; t < nt; ++t) {
;     const int cur = t & 1;
;     if (t + 1 < nt) G_STAGE(cur ^ 1, t + 1)
;     else if (has_next) {
;       char* sa_ = smem + wid * 1024;
;       char* sb_ = sa_ + G_TILE_B;
;       __builtin_amdgcn_global_load_lds((const unsigned*)(nA + o0), (unsigned*)(sa_), 16, 0, 0);
;       __builtin_amdgcn_global_load_lds((const unsigned*)(nB + o0), (unsigned*)(sb_), 16, 0, 0);
;       __builtin_amdgcn_global_load_lds((const unsigned*)(nA + o1), (unsigned*)(sa_ + 8192), 16, 0, 0);
;       __builtin_amdgcn_global_load_lds((const unsigned*)(nB + o1), (unsigned*)(sb_ + 8192), 16, 0, 0);
;       __builtin_amdgcn_global_load_lds((const unsigned*)(nA + o2), (unsigned*)(sa_ + 16384), 16, 0, 0);
;       __builtin_amdgcn_global_load_lds((const unsigned*)(nB + o2), (unsigned*)(sb_ + 16384), 16, 0, 0);
;       __builtin_amdgcn_global_load_lds((const unsigned*)(nA + o3), (unsigned*)(sa_ + 24576), 16, 0, 0);
;       __builtin_amdgcn_global_load_lds((const unsigned*)(nB + o3), (unsigned*)(sb_ + 24576), 16, 0, 0);
;     }
;     const char* sa = smem + cur * G_STAGE_B;
;     const char* sb = sa + G_TILE_B;
; #pragma unroll
;     for (int ks = 0; ks < 2; ++ks) {
;       s16x8 At[8], Bf[4];
; #pragma unroll
;       for (int m = 0; m < 8; ++m) At[m] = *(const s16x8*)(sa + g_lds_byte(wr * 128 + m * 16 + fr, ks * 32 + fq * 8));
; #pragma unroll
;       for (int n = 0; n < 4; ++n) Bf[n] = *(const s16x8*)(sb + g_lds_byte(wc * 64 + n * 16 + fr, ks * 32 + fq * 8));
; #pragma unroll
;       for (int m = 0; m < 8; ++m)
; #pragma unroll
;         for (int n = 0; n < 4; ++n)
;           acc[m][n] = __builtin_amdgcn_mfma_f32_16x16x32_bf16(__builtin_bit_cast(bf16x8, Bf[n]), __builtin_bit_cast(bf16x8, At[m]), acc[m][n], 0, 0, 0);
;     }
;     G_WAIT_V0();
;     __syncthreads();
;   }
.LBB0_631:
	s_and_b32 s13, s7, 0x10000
	v_or_b32_e32 v96, s13, v179
	v_add_u32_e32 v191, v96, v180
	v_add_u32_e32 v96, v96, v181
	ds_read_b128 v[130:133], v96 offset:32768
	ds_read_b128 v[138:141], v96 offset:34816
	ds_read_b128 v[182:185], v96 offset:36864
	ds_read_b128 v[186:189], v96 offset:38912
	ds_read_b128 v[134:137], v191
	ds_read_b128 v[204:207], v191 offset:2048
	ds_read_b128 v[208:211], v191 offset:4096
	ds_read_b128 v[212:215], v191 offset:6144
.Lmy_k3_top:
	s_and_b32 s12, s7, 0x10000
	s_xor_b32 s13, s12, 0x10000
	v_add_u32_e32 v252, s13, v166
	s_waitcnt lgkmcnt(3)
	v_mfma_f32_16x16x32_bf16 v[4:7], v[130:133], v[134:137], v[4:7]
	v_mfma_f32_16x16x32_bf16 v[114:117], v[138:141], v[134:137], v[114:117]
	v_mfma_f32_16x16x32_bf16 v[110:113], v[182:185], v[134:137], v[110:113]
	v_mfma_f32_16x16x32_bf16 v[106:109], v[186:189], v[134:137], v[106:109]
	ds_read_b128 v[134:137], v191 offset:8192
	v_readfirstlane_b32 s12, v252
	s_mov_b32 m0, s12
	v_lshl_add_u64 v[220:221], v[150:151], 0, s[10:11]
	global_load_lds_dwordx4 v[220:221], off
	s_waitcnt lgkmcnt(3)
	v_mfma_f32_16x16x32_bf16 v[102:105], v[130:133], v[204:207], v[102:105]
	v_mfma_f32_16x16x32_bf16 v[92:95], v[138:141], v[204:207], v[92:95]
	v_mfma_f32_16x16x32_bf16 v[76:79], v[182:185], v[204:207], v[76:79]
	v_mfma_f32_16x16x32_bf16 v[48:51], v[186:189], v[204:207], v[48:51]
	ds_read_b128 v[204:207], v191 offset:10240
	s_add_u32 m0, s12, 0x8000
	v_lshl_add_u64 v[220:221], v[158:159], 0, s[10:11]
	global_load_lds_dwordx4 v[220:221], off
	s_waitcnt lgkmcnt(3)
	v_mfma_f32_16x16x32_bf16 v[98:101], v[130:133], v[208:211], v[98:101]
	v_mfma_f32_16x16x32_bf16 v[84:87], v[138:141], v[208:211], v[84:87]
	v_mfma_f32_16x16x32_bf16 v[64:67], v[182:185], v[208:211], v[64:67]
	v_mfma_f32_16x16x32_bf16 v[36:39], v[186:189], v[208:211], v[36:39]
	ds_read_b128 v[208:211], v191 offset:12288
	ds_read_b128 v[216:219], v96 offset:33792
	s_add_u32 m0, s12, 0x2000
	v_lshl_add_u64 v[220:221], v[152:153], 0, s[10:11]
	global_load_lds_dwordx4 v[220:221], off
	s_waitcnt lgkmcnt(4)
	v_mfma_f32_16x16x32_bf16 v[88:91], v[130:133], v[212:215], v[88:91]
	v_mfma_f32_16x16x32_bf16 v[72:75], v[138:141], v[212:215], v[72:75]
	v_mfma_f32_16x16x32_bf16 v[52:55], v[182:185], v[212:215], v[52:55]
	v_mfma_f32_16x16x32_bf16 v[24:27], v[186:189], v[212:215], v[24:27]
	ds_read_b128 v[212:215], v191 offset:14336
	ds_read_b128 v[230:233], v96 offset:35840
	s_add_u32 m0, s12, 0xa000
	v_lshl_add_u64 v[220:221], v[160:161], 0, s[10:11]
	global_load_lds_dwordx4 v[220:221], off
	s_waitcnt lgkmcnt(5)
	v_mfma_f32_16x16x32_bf16 v[80:83], v[130:133], v[134:137], v[80:83]
	v_mfma_f32_16x16x32_bf16 v[60:63], v[138:141], v[134:137], v[60:63]
	v_mfma_f32_16x16x32_bf16 v[40:43], v[182:185], v[134:137], v[40:43]
	v_mfma_f32_16x16x32_bf16 v[16:19], v[186:189], v[134:137], v[16:19]
	ds_read_b128 v[134:137], v191 offset:1024
	ds_read_b128 v[244:247], v96 offset:37888
	s_add_u32 m0, s12, 0x4000
	v_lshl_add_u64 v[220:221], v[154:155], 0, s[10:11]
	global_load_lds_dwordx4 v[220:221], off
	s_waitcnt lgkmcnt(6)
	v_mfma_f32_16x16x32_bf16 v[68:71], v[130:133], v[204:207], v[68:71]
	v_mfma_f32_16x16x32_bf16 v[44:47], v[138:141], v[204:207], v[44:47]
	v_mfma_f32_16x16x32_bf16 v[28:31], v[182:185], v[204:207], v[28:31]
	v_mfma_f32_16x16x32_bf16 v[12:15], v[186:189], v[204:207], v[12:15]
	ds_read_b128 v[204:207], v191 offset:3072
	ds_read_b128 v[248:251], v96 offset:39936
	s_add_u32 m0, s12, 0xc000
	v_lshl_add_u64 v[220:221], v[162:163], 0, s[10:11]
	global_load_lds_dwordx4 v[220:221], off
	s_waitcnt lgkmcnt(7)
	v_mfma_f32_16x16x32_bf16 v[56:59], v[130:133], v[208:211], v[56:59]
	v_mfma_f32_16x16x32_bf16 v[32:35], v[138:141], v[208:211], v[32:35]
	v_mfma_f32_16x16x32_bf16 v[20:23], v[182:185], v[208:211], v[20:23]
	v_mfma_f32_16x16x32_bf16 v[8:11], v[186:189], v[208:211], v[8:11]
	ds_read_b128 v[208:211], v191 offset:5120
	s_add_u32 m0, s12, 0x6000
	v_lshl_add_u64 v[220:221], v[156:157], 0, s[10:11]
	global_load_lds_dwordx4 v[220:221], off
	s_waitcnt lgkmcnt(6)
	v_mfma_f32_16x16x32_bf16 v[122:125], v[130:133], v[212:215], v[122:125]
	v_mfma_f32_16x16x32_bf16 v[118:121], v[138:141], v[212:215], v[118:121]
	v_mfma_f32_16x16x32_bf16 v[126:129], v[182:185], v[212:215], v[126:129]
	v_mfma_f32_16x16x32_bf16 v[0:3], v[186:189], v[212:215], v[0:3]
	ds_read_b128 v[212:215], v191 offset:7168
	s_add_u32 m0, s12, 0xe000
	v_lshl_add_u64 v[220:221], v[164:165], 0, s[10:11]
	global_load_lds_dwordx4 v[220:221], off
	s_waitcnt lgkmcnt(5)
	v_mfma_f32_16x16x32_bf16 v[4:7], v[216:219], v[134:137], v[4:7]
	v_mfma_f32_16x16x32_bf16 v[114:117], v[230:233], v[134:137], v[114:117]
	s_waitcnt lgkmcnt(4)
	v_mfma_f32_16x16x32_bf16 v[110:113], v[244:247], v[134:137], v[110:113]
	s_waitcnt lgkmcnt(2)
	v_mfma_f32_16x16x32_bf16 v[106:109], v[248:251], v[134:137], v[106:109]
	ds_read_b128 v[134:137], v191 offset:9216
	v_mfma_f32_16x16x32_bf16 v[102:105], v[216:219], v[204:207], v[102:105]
	v_mfma_f32_16x16x32_bf16 v[92:95], v[230:233], v[204:207], v[92:95]
	v_mfma_f32_16x16x32_bf16 v[76:79], v[244:247], v[204:207], v[76:79]
	v_mfma_f32_16x16x32_bf16 v[48:51], v[248:251], v[204:207], v[48:51]
	ds_read_b128 v[204:207], v191 offset:11264
	s_waitcnt lgkmcnt(3)
	v_mfma_f32_16x16x32_bf16 v[98:101], v[216:219], v[208:211], v[98:101]
	v_mfma_f32_16x16x32_bf16 v[84:87], v[230:233], v[208:211], v[84:87]
	v_mfma_f32_16x16x32_bf16 v[64:67], v[244:247], v[208:211], v[64:67]
	v_mfma_f32_16x16x32_bf16 v[36:39], v[248:251], v[208:211], v[36:39]
	ds_read_b128 v[208:211], v191 offset:13312
	s_waitcnt lgkmcnt(3)
	v_mfma_f32_16x16x32_bf16 v[88:91], v[216:219], v[212:215], v[88:91]
	v_mfma_f32_16x16x32_bf16 v[72:75], v[230:233], v[212:215], v[72:75]
	v_mfma_f32_16x16x32_bf16 v[52:55], v[244:247], v[212:215], v[52:55]
	v_mfma_f32_16x16x32_bf16 v[24:27], v[248:251], v[212:215], v[24:27]
	ds_read_b128 v[212:215], v191 offset:15360
	s_waitcnt lgkmcnt(3)
	v_mfma_f32_16x16x32_bf16 v[80:83], v[216:219], v[134:137], v[80:83]
	v_mfma_f32_16x16x32_bf16 v[60:63], v[230:233], v[134:137], v[60:63]
	v_mfma_f32_16x16x32_bf16 v[40:43], v[244:247], v[134:137], v[40:43]
	v_mfma_f32_16x16x32_bf16 v[16:19], v[248:251], v[134:137], v[16:19]
	s_waitcnt lgkmcnt(2)
	v_mfma_f32_16x16x32_bf16 v[68:71], v[216:219], v[204:207], v[68:71]
	v_mfma_f32_16x16x32_bf16 v[44:47], v[230:233], v[204:207], v[44:47]
	v_mfma_f32_16x16x32_bf16 v[28:31], v[244:247], v[204:207], v[28:31]
	v_mfma_f32_16x16x32_bf16 v[12:15], v[248:251], v[204:207], v[12:15]
	s_waitcnt vmcnt(0)
	s_waitcnt vmcnt(0) lgkmcnt(0)
	s_barrier
; #define G_WAIT_V0() asm volatile("s_waitcnt vmcnt(0)" ::: "memory")
; __device__ __forceinline__ void g_kloop(const u16* __restrict__ Ab, const u16* __restrict__ Bb, const int K, char* smem, ...
;     ...
;   for (int t = 0; t < nt; ++t) {
;     const int cur = t & 1;
;     if (t + 1 < nt) G_STAGE(cur ^ 1, t + 1)
;     else if (has_next) {
;       char* sa_ = smem + wid * 1024;
;       char* sb_ = sa_ + G_TILE_B;
;       __builtin_amdgcn_global_load_lds((const unsigned*)(nA + o0), (unsigned*)(sa_), 16, 0, 0);
;       __builtin_amdgcn_global_load_lds((const unsigned*)(nB + o0), (unsigned*)(sb_), 16, 0, 0);
;       __builtin_amdgcn_global_load_lds((const unsigned*)(nA + o1), (unsigned*)(sa_ + 8192), 16, 0, 0);
;       __builtin_amdgcn_global_load_lds((const unsigned*)(nB + o1), (unsigned*)(sb_ + 8192), 16, 0, 0);
;       __builtin_amdgcn_global_load_lds((const unsigned*)(nA + o2), (unsigned*)(sa_ + 16384), 16, 0, 0);
;       __builtin_amdgcn_global_load_lds((const unsigned*)(nB + o2), (unsigned*)(sb_ + 16384), 16, 0, 0);
;       __builtin_amdgcn_global_load_lds((const unsigned*)(nA + o3), (unsigned*)(sa_ + 24576), 16, 0, 0);
;       __builtin_amdgcn_global_load_lds((const unsigned*)(nB + o3), (unsigned*)(sb_ + 24576), 16, 0, 0);
;     }
;     const char* sa = smem + cur * G_STAGE_B;
;     const char* sb = sa + G_TILE_B;
; #pragma unroll
;     for (int ks = 0; ks < 2; ++ks) {
;       s16x8 At[8], Bf[4];
; #pragma unroll
;       for (int m = 0; m < 8; ++m) At[m] = *(const s16x8*)(sa + g_lds_byte(wr * 128 + m * 16 + fr, ks * 32 + fq * 8));
; #pragma unroll
;       for (int n = 0; n < 4; ++n) Bf[n] = *(const s16x8*)(sb + g_lds_byte(wc * 64 + n * 16 + fr, ks * 32 + fq * 8));
; #pragma unroll
;       for (int m = 0; m < 8; ++m)
; #pragma unroll
;         for (int n = 0; n < 4; ++n)
;           acc[m][n] = __builtin_amdgcn_mfma_f32_16x16x32_bf16(__builtin_bit_cast(bf16x8, Bf[n]), __builtin_bit_cast(bf16x8, At[m]), acc[m][n], 0, 0, 0);
;     }
;     G_WAIT_V0();
;     __syncthreads();
;   }
	s_add_i32 s7, s7, 0x10000
	s_add_u32 s10, s10, 0x80
	s_addc_u32 s11, s11, 0
	s_and_b32 s13, s7, 0x10000
	v_or_b32_e32 v96, s13, v179
	v_add_u32_e32 v191, v96, v180
	v_add_u32_e32 v96, v96, v181
	ds_read_b128 v[130:133], v96 offset:32768
	ds_read_b128 v[138:141], v96 offset:34816
	ds_read_b128 v[182:185], v96 offset:36864
	ds_read_b128 v[186:189], v96 offset:38912
	ds_read_b128 v[134:137], v191
	ds_read_b128 v[204:207], v191 offset:2048
	v_mfma_f32_16x16x32_bf16 v[56:59], v[216:219], v[208:211], v[56:59]
	v_mfma_f32_16x16x32_bf16 v[32:35], v[230:233], v[208:211], v[32:35]
	v_mfma_f32_16x16x32_bf16 v[20:23], v[244:247], v[208:211], v[20:23]
	v_mfma_f32_16x16x32_bf16 v[8:11], v[248:251], v[208:211], v[8:11]
	ds_read_b128 v[208:211], v191 offset:4096
	v_mfma_f32_16x16x32_bf16 v[122:125], v[216:219], v[212:215], v[122:125]
	v_mfma_f32_16x16x32_bf16 v[118:121], v[230:233], v[212:215], v[118:121]
	v_mfma_f32_16x16x32_bf16 v[126:129], v[244:247], v[212:215], v[126:129]
	v_mfma_f32_16x16x32_bf16 v[0:3], v[248:251], v[212:215], v[0:3]
	ds_read_b128 v[212:215], v191 offset:6144
	s_cmpk_lg_i32 s10, 0x780
	s_cbranch_scc1 .Lmy_k3_top
	s_waitcnt lgkmcnt(0)
	s_andn2_b64 vcc, exec, s[8:9]
	s_cbranch_vccnz .LBB0_625
	s_lshl_b32 s8, s19, 8
	s_ashr_i32 s9, s8, 31
	s_lshl_b64 s[8:9], s[8:9], 11
	s_add_u32 s8, s86, s8
	s_addc_u32 s9, s87, s9
	s_lshl_b32 s10, s18, 8
	s_ashr_i32 s11, s10, 31
	s_lshl_b64 s[10:11], s[10:11], 11
	s_add_u32 s10, s14, s10
	v_lshlrev_b64 v[130:131], 1, v[142:143]
	v_add_u32_e32 v151, 0x8000, v166
	v_readfirstlane_b32 s7, v166
	s_addc_u32 s11, s15, s11
	v_lshl_add_u64 v[132:133], s[8:9], 0, v[130:131]
	v_add_u32_e32 v150, 0x2000, v166
	s_mov_b32 m0, s7
	v_readfirstlane_b32 s7, v151
	v_lshl_add_u64 v[130:131], s[10:11], 0, v[130:131]
	v_lshlrev_b64 v[134:135], 1, v[144:145]
	v_lshlrev_b64 v[142:143], 1, v[148:149]
	v_add_u32_e32 v149, 0xa000, v166
	global_load_lds_dwordx4 v[132:133], off
	s_mov_b32 m0, s7
	v_readfirstlane_b32 s7, v150
	v_lshl_add_u64 v[136:137], s[8:9], 0, v[134:135]
	v_add_u32_e32 v148, 0x4000, v166
	global_load_lds_dwordx4 v[130:131], off
	s_mov_b32 m0, s7
	v_readfirstlane_b32 s7, v149
	v_lshl_add_u64 v[134:135], s[10:11], 0, v[134:135]
	v_lshlrev_b64 v[138:139], 1, v[146:147]
	v_add_u32_e32 v147, 0xc000, v166
	global_load_lds_dwordx4 v[136:137], off
	s_mov_b32 m0, s7
	v_readfirstlane_b32 s7, v148
	v_lshl_add_u64 v[140:141], s[8:9], 0, v[138:139]
	v_add_u32_e32 v146, 0x6000, v166
	global_load_lds_dwordx4 v[134:135], off
	s_mov_b32 m0, s7
	v_readfirstlane_b32 s7, v147
	v_lshl_add_u64 v[138:139], s[10:11], 0, v[138:139]
	v_add_u32_e32 v96, 0xe000, v166
	global_load_lds_dwordx4 v[140:141], off
	s_mov_b32 m0, s7
	v_readfirstlane_b32 s7, v146
	v_lshl_add_u64 v[144:145], s[8:9], 0, v[142:143]
	global_load_lds_dwordx4 v[138:139], off
	s_mov_b32 m0, s7
	v_readfirstlane_b32 s7, v96
	v_lshl_add_u64 v[142:143], s[10:11], 0, v[142:143]
	global_load_lds_dwordx4 v[144:145], off
	s_mov_b32 m0, s7
	s_nop 0
	global_load_lds_dwordx4 v[142:143], off
	s_branch .LBB0_625
